# v4 + tap_table: filter_out values staged in LDS once per workgroup, read by ds_read_b64 broadcast instead of 128 uniform global loads per 16-k iteration; waits re-derived
# speedup vs baseline: 1.0287x; 1.0043x over previous
.LBB0_542:
	v_and_b32_e32 v255, 7, v0
	v_lshrrev_b32_e32 v254, 3, v0
	v_bfe_u32 v253, v255, 2, 1
	v_lshlrev_b32_e32 v254, 13, v254
	v_lshlrev_b32_e32 v253, 1, v253
	v_and_b32_e32 v250, 1, v255
	v_add_u32_e32 v253, 1, v253
	v_bfe_u32 v255, v255, 1, 1
	v_sub_u32_e32 v253, v253, v250
	v_lshl_add_u32 v254, v253, 11, v254
	v_lshl_add_u32 v254, v255, 10, v254
	global_load_dword v250, v254, s[16:17]
	v_lshlrev_b32_e32 v255, 2, v0
	v_mov_b32_e32 v253, 0
	s_waitcnt vmcnt(0)
	ds_write_b32 v255, v250
	s_waitcnt lgkmcnt(0)
	s_barrier
	s_mov_b64 s[4:5], 0
	v_mov_b32_e32 v12, 0
	v_mov_b32_e32 v13, v5
	v_mov_b32_e32 v24, 0
	v_mov_b32_e32 v25, v5
	v_mov_b32_e32 v14, 0
	v_mov_b32_e32 v15, v5
	v_mov_b32_e32 v28, 0
	v_mov_b32_e32 v29, v5
	v_mov_b32_e32 v16, 0
	v_mov_b32_e32 v17, v5
	v_mov_b32_e32 v30, 0
	v_mov_b32_e32 v31, v5
	v_mov_b32_e32 v18, 0
	v_mov_b32_e32 v19, v5
	v_mov_b32_e32 v38, 0
	v_mov_b32_e32 v39, v5
	v_mov_b32_e32 v40, 0
	v_mov_b32_e32 v41, v5
	v_mov_b32_e32 v20, 0
	v_mov_b32_e32 v21, v5
	v_mov_b32_e32 v44, 0
	v_mov_b32_e32 v45, v5
	v_mov_b32_e32 v22, 0
	v_mov_b32_e32 v23, v5
	v_mov_b32_e32 v46, 0
	v_mov_b32_e32 v47, v5
	v_mov_b32_e32 v26, 0
	v_mov_b32_e32 v27, v5
	v_mov_b32_e32 v48, 0
	v_mov_b32_e32 v49, v5
	v_mov_b32_e32 v50, 0
	v_mov_b32_e32 v51, v5
.LBB0_543:
	v_lshl_add_u64 v[158:159], v[10:11], 0, s[4:5]
	s_mov_b32 s3, 0x180000
	v_add_co_u32_e32 v32, vcc, s3, v158
	s_mov_b32 s3, 0x181000
	s_nop 0
	v_addc_co_u32_e32 v33, vcc, 0, v159, vcc
	v_add_co_u32_e32 v42, vcc, s3, v158
	s_add_u32 s8, s16, s4
	s_nop 0
	v_addc_co_u32_e32 v43, vcc, 0, v159, vcc
	global_load_dword v36, v[42:43], off offset:-4096
	global_load_dword v34, v[32:33], off offset:2048
	s_nop 0
	global_load_dword v32, v[42:43], off
	global_load_dword v4, v[42:43], off offset:2048
	s_addc_u32 s9, s17, s5
	ds_read_b64 v[58:59], v253 offset:0
	ds_read_b64 v[54:55], v253 offset:16
	ds_read_b64 v[52:53], v253 offset:8
	ds_read_b64 v[42:43], v253 offset:24
	s_mov_b32 s3, 0x182000
	v_add_co_u32_e32 v62, vcc, s3, v158
	s_mov_b32 s3, 0x183000
	s_nop 0
	v_addc_co_u32_e32 v63, vcc, 0, v159, vcc
	v_add_co_u32_e32 v68, vcc, s3, v158
	s_mov_b32 s3, 0x184000
	s_nop 0
	v_addc_co_u32_e32 v69, vcc, 0, v159, vcc
	v_add_co_u32_e32 v74, vcc, s3, v158
	s_mov_b32 s3, 0x185000
	s_nop 0
	v_addc_co_u32_e32 v75, vcc, 0, v159, vcc
	v_add_co_u32_e32 v84, vcc, s3, v158
	s_mov_b32 s3, 0x186000
	s_nop 0
	v_addc_co_u32_e32 v85, vcc, 0, v159, vcc
	v_add_co_u32_e32 v116, vcc, s3, v158
	s_mov_b32 s3, 0x187000
	s_nop 0
	v_addc_co_u32_e32 v117, vcc, 0, v159, vcc
	v_add_co_u32_e32 v122, vcc, s3, v158
	s_mov_b32 s3, 0x188000
	s_nop 0
	v_addc_co_u32_e32 v123, vcc, 0, v159, vcc
	v_add_co_u32_e32 v138, vcc, s3, v158
	global_load_dword v66, v[68:69], off offset:-4096
	global_load_dword v64, v[62:63], off offset:2048
	global_load_dword v60, v[68:69], off
	global_load_dword v56, v[68:69], off offset:2048
	ds_read_b64 v[72:73], v253 offset:32
	ds_read_b64 v[70:71], v253 offset:48
	s_nop 0
	ds_read_b64 v[68:69], v253 offset:40
	ds_read_b64 v[62:63], v253 offset:56
	v_addc_co_u32_e32 v139, vcc, 0, v159, vcc
	global_load_dword v76, v[84:85], off offset:-4096
	global_load_dword v78, v[74:75], off offset:2048
	global_load_dword v80, v[84:85], off
	s_nop 0
	global_load_dword v74, v[84:85], off offset:2048
	s_nop 0
	ds_read_b64 v[84:85], v253 offset:64
	ds_read_b64 v[94:95], v253 offset:80
	ds_read_b64 v[104:105], v253 offset:72
	ds_read_b64 v[112:113], v253 offset:88
	v_add_co_u32_e32 v140, vcc, s18, v158
	global_load_dword v82, v[122:123], off offset:-4096
	global_load_dword v86, v[116:117], off offset:2048
	global_load_dword v88, v[122:123], off
	global_load_dword v90, v[122:123], off offset:2048
	s_nop 0
	ds_read_b64 v[116:117], v253 offset:96
	ds_read_b64 v[122:123], v253 offset:112
	ds_read_b64 v[126:127], v253 offset:104
	ds_read_b64 v[130:131], v253 offset:120
	v_addc_co_u32_e32 v141, vcc, 0, v159, vcc
	global_load_dword v92, v[140:141], off offset:-4096
	global_load_dword v96, v[138:139], off offset:2048
	global_load_dword v98, v[140:141], off
	global_load_dword v100, v[140:141], off offset:2048
	s_nop 0
	ds_read_b64 v[138:139], v253 offset:128
	s_add_u32 s4, s4, 0x20000
	s_addc_u32 s5, s5, 0
	s_cmp_eq_u32 s4, 0x80000
	s_waitcnt vmcnt(16) lgkmcnt(15)
	v_pk_fma_f32 v[50:51], v[36:37], v[58:59], v[50:51] op_sel_hi:[0,1,1]
	v_pk_fma_f32 v[26:27], v[34:35], v[58:59], v[26:27] op_sel_hi:[0,1,1]
	v_pk_fma_f32 v[22:23], v[32:33], v[58:59], v[22:23] op_sel_hi:[0,1,1]
	v_pk_fma_f32 v[20:21], v[4:5], v[58:59], v[20:21] op_sel_hi:[0,1,1]
	ds_read_b64 v[58:59], v253 offset:144
	s_waitcnt vmcnt(16) lgkmcnt(15)
	v_pk_fma_f32 v[48:49], v[36:37], v[54:55], v[48:49] op_sel_hi:[0,1,1]
	v_pk_fma_f32 v[46:47], v[34:35], v[54:55], v[46:47] op_sel_hi:[0,1,1]
	v_pk_fma_f32 v[44:45], v[32:33], v[54:55], v[44:45] op_sel_hi:[0,1,1]
	v_pk_fma_f32 v[40:41], v[4:5], v[54:55], v[40:41] op_sel_hi:[0,1,1]
	ds_read_b64 v[54:55], v253 offset:136
	s_waitcnt vmcnt(16) lgkmcnt(15)
	v_pk_fma_f32 v[38:39], v[36:37], v[52:53], v[38:39] op_sel_hi:[0,1,1]
	v_pk_fma_f32 v[30:31], v[34:35], v[52:53], v[30:31] op_sel_hi:[0,1,1]
	v_pk_fma_f32 v[28:29], v[32:33], v[52:53], v[28:29] op_sel_hi:[0,1,1]
	v_pk_fma_f32 v[24:25], v[4:5], v[52:53], v[24:25] op_sel_hi:[0,1,1]
	ds_read_b64 v[52:53], v253 offset:152
	s_waitcnt vmcnt(16) lgkmcnt(15)
	v_pk_fma_f32 v[18:19], v[36:37], v[42:43], v[18:19] op_sel_hi:[0,1,1]
	v_pk_fma_f32 v[16:17], v[34:35], v[42:43], v[16:17] op_sel_hi:[0,1,1]
	v_pk_fma_f32 v[14:15], v[32:33], v[42:43], v[14:15] op_sel_hi:[0,1,1]
	v_pk_fma_f32 v[12:13], v[4:5], v[42:43], v[12:13] op_sel_hi:[0,1,1]
	v_add_co_u32_e32 v32, vcc, s19, v158
	s_waitcnt vmcnt(12) lgkmcnt(15)
	v_pk_fma_f32 v[26:27], v[64:65], v[72:73], v[26:27] op_sel_hi:[0,1,1]
	v_addc_co_u32_e32 v33, vcc, 0, v159, vcc
	s_waitcnt vmcnt(12) lgkmcnt(14)
	v_pk_fma_f32 v[48:49], v[66:67], v[70:71], v[48:49] op_sel_hi:[0,1,1]
	v_pk_fma_f32 v[46:47], v[64:65], v[70:71], v[46:47] op_sel_hi:[0,1,1]
	v_pk_fma_f32 v[44:45], v[60:61], v[70:71], v[44:45] op_sel_hi:[0,1,1]
	s_waitcnt vmcnt(12) lgkmcnt(12)
	v_pk_fma_f32 v[18:19], v[66:67], v[62:63], v[18:19] op_sel_hi:[0,1,1]
	v_pk_fma_f32 v[16:17], v[64:65], v[62:63], v[16:17] op_sel_hi:[0,1,1]
	v_pk_fma_f32 v[14:15], v[60:61], v[62:63], v[14:15] op_sel_hi:[0,1,1]
	v_pk_fma_f32 v[12:13], v[56:57], v[62:63], v[12:13] op_sel_hi:[0,1,1]
	s_waitcnt vmcnt(8) lgkmcnt(8)
	v_pk_fma_f32 v[18:19], v[76:77], v[112:113], v[18:19] op_sel_hi:[0,1,1]
	v_pk_fma_f32 v[16:17], v[78:79], v[112:113], v[16:17] op_sel_hi:[0,1,1]
	v_pk_fma_f32 v[14:15], v[80:81], v[112:113], v[14:15] op_sel_hi:[0,1,1]
	v_pk_fma_f32 v[12:13], v[74:75], v[112:113], v[12:13] op_sel_hi:[0,1,1]
	s_waitcnt vmcnt(4) lgkmcnt(4)
	v_pk_fma_f32 v[18:19], v[82:83], v[130:131], v[18:19] op_sel_hi:[0,1,1]
	v_pk_fma_f32 v[16:17], v[86:87], v[130:131], v[16:17] op_sel_hi:[0,1,1]
	v_pk_fma_f32 v[14:15], v[88:89], v[130:131], v[14:15] op_sel_hi:[0,1,1]
	v_pk_fma_f32 v[12:13], v[90:91], v[130:131], v[12:13] op_sel_hi:[0,1,1]
	v_pk_fma_f32 v[40:41], v[56:57], v[70:71], v[40:41] op_sel_hi:[0,1,1]
	v_pk_fma_f32 v[48:49], v[76:77], v[94:95], v[48:49] op_sel_hi:[0,1,1]
	v_pk_fma_f32 v[46:47], v[78:79], v[94:95], v[46:47] op_sel_hi:[0,1,1]
	v_pk_fma_f32 v[44:45], v[80:81], v[94:95], v[44:45] op_sel_hi:[0,1,1]
	v_pk_fma_f32 v[40:41], v[74:75], v[94:95], v[40:41] op_sel_hi:[0,1,1]
	v_pk_fma_f32 v[48:49], v[82:83], v[122:123], v[48:49] op_sel_hi:[0,1,1]
	v_pk_fma_f32 v[46:47], v[86:87], v[122:123], v[46:47] op_sel_hi:[0,1,1]
	v_pk_fma_f32 v[44:45], v[88:89], v[122:123], v[44:45] op_sel_hi:[0,1,1]
	v_pk_fma_f32 v[40:41], v[90:91], v[122:123], v[40:41] op_sel_hi:[0,1,1]
	v_pk_fma_f32 v[38:39], v[66:67], v[68:69], v[38:39] op_sel_hi:[0,1,1]
	v_pk_fma_f32 v[30:31], v[64:65], v[68:69], v[30:31] op_sel_hi:[0,1,1]
	v_pk_fma_f32 v[28:29], v[60:61], v[68:69], v[28:29] op_sel_hi:[0,1,1]
	v_pk_fma_f32 v[24:25], v[56:57], v[68:69], v[24:25] op_sel_hi:[0,1,1]
	v_pk_fma_f32 v[38:39], v[76:77], v[104:105], v[38:39] op_sel_hi:[0,1,1]
	v_pk_fma_f32 v[30:31], v[78:79], v[104:105], v[30:31] op_sel_hi:[0,1,1]
	v_pk_fma_f32 v[28:29], v[80:81], v[104:105], v[28:29] op_sel_hi:[0,1,1]
	v_pk_fma_f32 v[24:25], v[74:75], v[104:105], v[24:25] op_sel_hi:[0,1,1]
	v_pk_fma_f32 v[38:39], v[82:83], v[126:127], v[38:39] op_sel_hi:[0,1,1]
	v_pk_fma_f32 v[30:31], v[86:87], v[126:127], v[30:31] op_sel_hi:[0,1,1]
	v_pk_fma_f32 v[28:29], v[88:89], v[126:127], v[28:29] op_sel_hi:[0,1,1]
	v_pk_fma_f32 v[24:25], v[90:91], v[126:127], v[24:25] op_sel_hi:[0,1,1]
	v_pk_fma_f32 v[50:51], v[66:67], v[72:73], v[50:51] op_sel_hi:[0,1,1]
	v_pk_fma_f32 v[22:23], v[60:61], v[72:73], v[22:23] op_sel_hi:[0,1,1]
	v_pk_fma_f32 v[20:21], v[56:57], v[72:73], v[20:21] op_sel_hi:[0,1,1]
	v_pk_fma_f32 v[20:21], v[74:75], v[84:85], v[20:21] op_sel_hi:[0,1,1]
	v_pk_fma_f32 v[50:51], v[76:77], v[84:85], v[50:51] op_sel_hi:[0,1,1]
	v_pk_fma_f32 v[26:27], v[78:79], v[84:85], v[26:27] op_sel_hi:[0,1,1]
	v_pk_fma_f32 v[22:23], v[80:81], v[84:85], v[22:23] op_sel_hi:[0,1,1]
	v_pk_fma_f32 v[50:51], v[82:83], v[116:117], v[50:51] op_sel_hi:[0,1,1]
	v_pk_fma_f32 v[26:27], v[86:87], v[116:117], v[26:27] op_sel_hi:[0,1,1]
	v_pk_fma_f32 v[22:23], v[88:89], v[116:117], v[22:23] op_sel_hi:[0,1,1]
	v_pk_fma_f32 v[20:21], v[90:91], v[116:117], v[20:21] op_sel_hi:[0,1,1]
	s_waitcnt vmcnt(0) lgkmcnt(3)
	v_pk_fma_f32 v[50:51], v[92:93], v[138:139], v[50:51] op_sel_hi:[0,1,1]
	v_pk_fma_f32 v[26:27], v[96:97], v[138:139], v[26:27] op_sel_hi:[0,1,1]
	v_pk_fma_f32 v[22:23], v[98:99], v[138:139], v[22:23] op_sel_hi:[0,1,1]
	v_pk_fma_f32 v[20:21], v[100:101], v[138:139], v[20:21] op_sel_hi:[0,1,1]
	s_waitcnt vmcnt(0) lgkmcnt(2)
	v_pk_fma_f32 v[48:49], v[92:93], v[58:59], v[48:49] op_sel_hi:[0,1,1]
	v_pk_fma_f32 v[46:47], v[96:97], v[58:59], v[46:47] op_sel_hi:[0,1,1]
	s_waitcnt vmcnt(0) lgkmcnt(1)
	v_pk_fma_f32 v[38:39], v[92:93], v[54:55], v[38:39] op_sel_hi:[0,1,1]
	v_pk_fma_f32 v[30:31], v[96:97], v[54:55], v[30:31] op_sel_hi:[0,1,1]
	v_pk_fma_f32 v[28:29], v[98:99], v[54:55], v[28:29] op_sel_hi:[0,1,1]
	v_pk_fma_f32 v[24:25], v[100:101], v[54:55], v[24:25] op_sel_hi:[0,1,1]
	v_pk_fma_f32 v[44:45], v[98:99], v[58:59], v[44:45] op_sel_hi:[0,1,1]
	s_waitcnt vmcnt(0) lgkmcnt(0)
	v_pk_fma_f32 v[18:19], v[92:93], v[52:53], v[18:19] op_sel_hi:[0,1,1]
	v_pk_fma_f32 v[16:17], v[96:97], v[52:53], v[16:17] op_sel_hi:[0,1,1]
	v_pk_fma_f32 v[14:15], v[98:99], v[52:53], v[14:15] op_sel_hi:[0,1,1]
	v_pk_fma_f32 v[12:13], v[100:101], v[52:53], v[12:13] op_sel_hi:[0,1,1]
	v_add_co_u32_e32 v52, vcc, s20, v158
	v_pk_fma_f32 v[40:41], v[100:101], v[58:59], v[40:41] op_sel_hi:[0,1,1]
	s_nop 0
	v_addc_co_u32_e32 v53, vcc, 0, v159, vcc
	global_load_dword v42, v[52:53], off offset:-4096
	global_load_dword v36, v[32:33], off offset:2048
	global_load_dword v34, v[52:53], off
	global_load_dword v4, v[52:53], off offset:2048
	ds_read_b64 v[164:165], v253 offset:160
	ds_read_b64 v[122:123], v253 offset:176
	ds_read_b64 v[112:113], v253 offset:168
	ds_read_b64 v[32:33], v253 offset:184
	v_add_co_u32_e32 v52, vcc, s21, v158
	s_waitcnt vmcnt(0) lgkmcnt(3)
	v_pk_fma_f32 v[50:51], v[42:43], v[164:165], v[50:51] op_sel_hi:[0,1,1]
	v_addc_co_u32_e32 v53, vcc, 0, v159, vcc
	v_add_co_u32_e32 v54, vcc, s22, v158
	v_pk_fma_f32 v[26:27], v[36:37], v[164:165], v[26:27] op_sel_hi:[0,1,1]
	s_nop 0
	v_addc_co_u32_e32 v55, vcc, 0, v159, vcc
	v_add_co_u32_e32 v62, vcc, s23, v158
	global_load_dword v60, v[54:55], off offset:-4096
	global_load_dword v58, v[52:53], off offset:2048
	global_load_dword v56, v[54:55], off
	s_nop 0
	global_load_dword v52, v[54:55], off offset:2048
	ds_read_b64 v[172:173], v253 offset:192
	ds_read_b64 v[138:139], v253 offset:208
	ds_read_b64 v[126:127], v253 offset:200
	ds_read_b64 v[54:55], v253 offset:216
	v_addc_co_u32_e32 v63, vcc, 0, v159, vcc
	v_add_co_u32_e32 v64, vcc, s24, v158
	v_pk_fma_f32 v[22:23], v[34:35], v[164:165], v[22:23] op_sel_hi:[0,1,1]
	s_nop 0
	v_addc_co_u32_e32 v65, vcc, 0, v159, vcc
	v_add_co_u32_e32 v72, vcc, s25, v158
	global_load_dword v70, v[64:65], off offset:-4096
	global_load_dword v68, v[62:63], off offset:2048
	global_load_dword v66, v[64:65], off
	s_nop 0
	global_load_dword v62, v[64:65], off offset:2048
	ds_read_b64 v[176:177], v253 offset:224
	ds_read_b64 v[150:151], v253 offset:240
	ds_read_b64 v[140:141], v253 offset:232
	ds_read_b64 v[64:65], v253 offset:248
	v_addc_co_u32_e32 v73, vcc, 0, v159, vcc
	v_add_co_u32_e32 v74, vcc, s26, v158
	v_pk_fma_f32 v[20:21], v[4:5], v[164:165], v[20:21] op_sel_hi:[0,1,1]
	s_nop 0
	v_addc_co_u32_e32 v75, vcc, 0, v159, vcc
	v_add_co_u32_e32 v84, vcc, s27, v158
	global_load_dword v80, v[74:75], off offset:-4096
	global_load_dword v78, v[72:73], off offset:2048
	global_load_dword v76, v[74:75], off
	s_nop 0
	global_load_dword v72, v[74:75], off offset:2048
	ds_read_b64 v[184:185], v253 offset:256
	ds_read_b64 v[156:157], v253 offset:272
	ds_read_b64 v[154:155], v253 offset:264
	ds_read_b64 v[74:75], v253 offset:280
	v_addc_co_u32_e32 v85, vcc, 0, v159, vcc
	v_add_co_u32_e32 v94, vcc, s28, v158
	s_waitcnt vmcnt(12) lgkmcnt(14)
	v_pk_fma_f32 v[48:49], v[42:43], v[122:123], v[48:49] op_sel_hi:[0,1,1]
	v_addc_co_u32_e32 v95, vcc, 0, v159, vcc
	global_load_dword v90, v[94:95], off offset:-4096
	global_load_dword v88, v[84:85], off offset:2048
	global_load_dword v86, v[94:95], off
	global_load_dword v82, v[94:95], off offset:2048
	ds_read_b64 v[190:191], v253 offset:288
	ds_read_b64 v[162:163], v253 offset:304
	ds_read_b64 v[160:161], v253 offset:296
	ds_read_b64 v[84:85], v253 offset:312
	v_add_co_u32_e32 v94, vcc, s29, v158
	v_pk_fma_f32 v[46:47], v[36:37], v[122:123], v[46:47] op_sel_hi:[0,1,1]
	s_nop 0
	v_addc_co_u32_e32 v95, vcc, 0, v159, vcc
	v_add_co_u32_e32 v104, vcc, s30, v158
	v_pk_fma_f32 v[44:45], v[34:35], v[122:123], v[44:45] op_sel_hi:[0,1,1]
	s_nop 0
	v_addc_co_u32_e32 v105, vcc, 0, v159, vcc
	global_load_dword v100, v[104:105], off offset:-4096
	global_load_dword v98, v[94:95], off offset:2048
	global_load_dword v96, v[104:105], off
	global_load_dword v92, v[104:105], off offset:2048
	ds_read_b64 v[196:197], v253 offset:320
	ds_read_b64 v[168:169], v253 offset:336
	ds_read_b64 v[166:167], v253 offset:328
	ds_read_b64 v[94:95], v253 offset:344
	v_add_co_u32_e32 v104, vcc, s31, v158
	v_pk_fma_f32 v[40:41], v[4:5], v[122:123], v[40:41] op_sel_hi:[0,1,1]
	s_nop 0
	v_addc_co_u32_e32 v105, vcc, 0, v159, vcc
	v_add_co_u32_e32 v116, vcc, s33, v158
	s_waitcnt vmcnt(20) lgkmcnt(15)
	v_pk_fma_f32 v[38:39], v[42:43], v[112:113], v[38:39] op_sel_hi:[0,1,1]
	v_addc_co_u32_e32 v117, vcc, 0, v159, vcc
	global_load_dword v110, v[116:117], off offset:-4096
	global_load_dword v108, v[104:105], off offset:2048
	global_load_dword v106, v[116:117], off
	global_load_dword v102, v[116:117], off offset:2048
	ds_read_b64 v[198:199], v253 offset:352
	ds_read_b64 v[174:175], v253 offset:368
	ds_read_b64 v[170:171], v253 offset:360
	ds_read_b64 v[104:105], v253 offset:376
	v_add_co_u32_e32 v116, vcc, s34, v158
	v_pk_fma_f32 v[30:31], v[36:37], v[112:113], v[30:31] op_sel_hi:[0,1,1]
	s_nop 0
	v_addc_co_u32_e32 v117, vcc, 0, v159, vcc
	v_add_co_u32_e32 v130, vcc, s35, v158
	v_pk_fma_f32 v[28:29], v[34:35], v[112:113], v[28:29] op_sel_hi:[0,1,1]
	s_nop 0
	v_addc_co_u32_e32 v131, vcc, 0, v159, vcc
	global_load_dword v124, v[130:131], off offset:-4096
	global_load_dword v120, v[116:117], off offset:2048
	global_load_dword v118, v[130:131], off
	global_load_dword v114, v[130:131], off offset:2048
	ds_read_b64 v[200:201], v253 offset:384
	ds_read_b64 v[182:183], v253 offset:400
	ds_read_b64 v[180:181], v253 offset:392
	ds_read_b64 v[116:117], v253 offset:408
	v_add_co_u32_e32 v130, vcc, s42, v158
	v_pk_fma_f32 v[24:25], v[4:5], v[112:113], v[24:25] op_sel_hi:[0,1,1]
	s_nop 0
	v_addc_co_u32_e32 v131, vcc, 0, v159, vcc
	v_add_co_u32_e32 v144, vcc, s43, v158
	s_waitcnt vmcnt(20) lgkmcnt(15)
	v_pk_fma_f32 v[18:19], v[42:43], v[32:33], v[18:19] op_sel_hi:[0,1,1]
	v_addc_co_u32_e32 v145, vcc, 0, v159, vcc
	global_load_dword v136, v[144:145], off offset:-4096
	global_load_dword v134, v[130:131], off offset:2048
	global_load_dword v132, v[144:145], off
	global_load_dword v128, v[144:145], off offset:2048
	ds_read_b64 v[208:209], v253 offset:416
	ds_read_b64 v[188:189], v253 offset:432
	ds_read_b64 v[186:187], v253 offset:424
	ds_read_b64 v[130:131], v253 offset:440
	v_add_co_u32_e32 v144, vcc, s44, v158
	v_pk_fma_f32 v[16:17], v[36:37], v[32:33], v[16:17] op_sel_hi:[0,1,1]
	s_nop 0
	v_addc_co_u32_e32 v145, vcc, 0, v159, vcc
	v_add_co_u32_e32 v192, vcc, s45, v158
	v_pk_fma_f32 v[14:15], v[34:35], v[32:33], v[14:15] op_sel_hi:[0,1,1]
	s_nop 0
	v_addc_co_u32_e32 v193, vcc, 0, v159, vcc
	v_add_co_u32_e32 v202, vcc, s46, v158
	global_load_dword v152, v[192:193], off offset:-4096
	global_load_dword v148, v[144:145], off offset:2048
	global_load_dword v146, v[192:193], off
	global_load_dword v142, v[192:193], off offset:2048
	ds_read_b64 v[210:211], v253 offset:448
	ds_read_b64 v[194:195], v253 offset:464
	s_nop 0
	ds_read_b64 v[192:193], v253 offset:456
	ds_read_b64 v[144:145], v253 offset:472
	v_addc_co_u32_e32 v203, vcc, 0, v159, vcc
	v_add_co_u32_e32 v212, vcc, s47, v158
	v_pk_fma_f32 v[12:13], v[4:5], v[32:33], v[12:13] op_sel_hi:[0,1,1]
	s_nop 0
	v_addc_co_u32_e32 v213, vcc, 0, v159, vcc
	global_load_dword v158, v[212:213], off offset:-4096
	global_load_dword v206, v[202:203], off offset:2048
	global_load_dword v204, v[212:213], off
	s_nop 0
	global_load_dword v202, v[212:213], off offset:2048
	s_nop 0
	ds_read_b64 v[212:213], v253 offset:480
	ds_read_b64 v[164:165], v253 offset:496
	ds_read_b64 v[122:123], v253 offset:488
	ds_read_b64 v[112:113], v253 offset:504
	v_pk_fma_f32 v[50:51], v[60:61], v[172:173], v[50:51] op_sel_hi:[0,1,1]
	v_pk_fma_f32 v[26:27], v[58:59], v[172:173], v[26:27] op_sel_hi:[0,1,1]
	v_pk_fma_f32 v[22:23], v[56:57], v[172:173], v[22:23] op_sel_hi:[0,1,1]
	v_pk_fma_f32 v[20:21], v[52:53], v[172:173], v[20:21] op_sel_hi:[0,1,1]
	v_pk_fma_f32 v[48:49], v[60:61], v[138:139], v[48:49] op_sel_hi:[0,1,1]
	v_pk_fma_f32 v[46:47], v[58:59], v[138:139], v[46:47] op_sel_hi:[0,1,1]
	v_pk_fma_f32 v[44:45], v[56:57], v[138:139], v[44:45] op_sel_hi:[0,1,1]
	v_pk_fma_f32 v[40:41], v[52:53], v[138:139], v[40:41] op_sel_hi:[0,1,1]
	v_pk_fma_f32 v[38:39], v[60:61], v[126:127], v[38:39] op_sel_hi:[0,1,1]
	v_pk_fma_f32 v[30:31], v[58:59], v[126:127], v[30:31] op_sel_hi:[0,1,1]
	v_pk_fma_f32 v[28:29], v[56:57], v[126:127], v[28:29] op_sel_hi:[0,1,1]
	v_pk_fma_f32 v[24:25], v[52:53], v[126:127], v[24:25] op_sel_hi:[0,1,1]
	v_pk_fma_f32 v[18:19], v[60:61], v[54:55], v[18:19] op_sel_hi:[0,1,1]
	v_pk_fma_f32 v[16:17], v[58:59], v[54:55], v[16:17] op_sel_hi:[0,1,1]
	v_pk_fma_f32 v[14:15], v[56:57], v[54:55], v[14:15] op_sel_hi:[0,1,1]
	v_pk_fma_f32 v[12:13], v[52:53], v[54:55], v[12:13] op_sel_hi:[0,1,1]
	v_pk_fma_f32 v[50:51], v[70:71], v[176:177], v[50:51] op_sel_hi:[0,1,1]
	v_pk_fma_f32 v[26:27], v[68:69], v[176:177], v[26:27] op_sel_hi:[0,1,1]
	v_pk_fma_f32 v[22:23], v[66:67], v[176:177], v[22:23] op_sel_hi:[0,1,1]
	v_pk_fma_f32 v[20:21], v[62:63], v[176:177], v[20:21] op_sel_hi:[0,1,1]
	v_pk_fma_f32 v[48:49], v[70:71], v[150:151], v[48:49] op_sel_hi:[0,1,1]
	v_pk_fma_f32 v[46:47], v[68:69], v[150:151], v[46:47] op_sel_hi:[0,1,1]
	v_pk_fma_f32 v[44:45], v[66:67], v[150:151], v[44:45] op_sel_hi:[0,1,1]
	v_pk_fma_f32 v[40:41], v[62:63], v[150:151], v[40:41] op_sel_hi:[0,1,1]
	v_pk_fma_f32 v[38:39], v[70:71], v[140:141], v[38:39] op_sel_hi:[0,1,1]
	v_pk_fma_f32 v[30:31], v[68:69], v[140:141], v[30:31] op_sel_hi:[0,1,1]
	v_pk_fma_f32 v[28:29], v[66:67], v[140:141], v[28:29] op_sel_hi:[0,1,1]
	v_pk_fma_f32 v[24:25], v[62:63], v[140:141], v[24:25] op_sel_hi:[0,1,1]
	s_waitcnt vmcnt(20) lgkmcnt(15)
	v_pk_fma_f32 v[18:19], v[70:71], v[64:65], v[18:19] op_sel_hi:[0,1,1]
	v_pk_fma_f32 v[16:17], v[68:69], v[64:65], v[16:17] op_sel_hi:[0,1,1]
	v_pk_fma_f32 v[14:15], v[66:67], v[64:65], v[14:15] op_sel_hi:[0,1,1]
	v_pk_fma_f32 v[12:13], v[62:63], v[64:65], v[12:13] op_sel_hi:[0,1,1]
	v_pk_fma_f32 v[50:51], v[80:81], v[184:185], v[50:51] op_sel_hi:[0,1,1]
	v_pk_fma_f32 v[26:27], v[78:79], v[184:185], v[26:27] op_sel_hi:[0,1,1]
	v_pk_fma_f32 v[22:23], v[76:77], v[184:185], v[22:23] op_sel_hi:[0,1,1]
	v_pk_fma_f32 v[20:21], v[72:73], v[184:185], v[20:21] op_sel_hi:[0,1,1]
	v_pk_fma_f32 v[48:49], v[80:81], v[156:157], v[48:49] op_sel_hi:[0,1,1]
	v_pk_fma_f32 v[46:47], v[78:79], v[156:157], v[46:47] op_sel_hi:[0,1,1]
	v_pk_fma_f32 v[44:45], v[76:77], v[156:157], v[44:45] op_sel_hi:[0,1,1]
	v_pk_fma_f32 v[40:41], v[72:73], v[156:157], v[40:41] op_sel_hi:[0,1,1]
	v_pk_fma_f32 v[38:39], v[80:81], v[154:155], v[38:39] op_sel_hi:[0,1,1]
	v_pk_fma_f32 v[30:31], v[78:79], v[154:155], v[30:31] op_sel_hi:[0,1,1]
	v_pk_fma_f32 v[28:29], v[76:77], v[154:155], v[28:29] op_sel_hi:[0,1,1]
	v_pk_fma_f32 v[24:25], v[72:73], v[154:155], v[24:25] op_sel_hi:[0,1,1]
	v_pk_fma_f32 v[18:19], v[80:81], v[74:75], v[18:19] op_sel_hi:[0,1,1]
	v_pk_fma_f32 v[16:17], v[78:79], v[74:75], v[16:17] op_sel_hi:[0,1,1]
	v_pk_fma_f32 v[14:15], v[76:77], v[74:75], v[14:15] op_sel_hi:[0,1,1]
	v_pk_fma_f32 v[12:13], v[72:73], v[74:75], v[12:13] op_sel_hi:[0,1,1]
	v_pk_fma_f32 v[50:51], v[90:91], v[190:191], v[50:51] op_sel_hi:[0,1,1]
	v_pk_fma_f32 v[26:27], v[88:89], v[190:191], v[26:27] op_sel_hi:[0,1,1]
	v_pk_fma_f32 v[22:23], v[86:87], v[190:191], v[22:23] op_sel_hi:[0,1,1]
	v_pk_fma_f32 v[20:21], v[82:83], v[190:191], v[20:21] op_sel_hi:[0,1,1]
	v_pk_fma_f32 v[48:49], v[90:91], v[162:163], v[48:49] op_sel_hi:[0,1,1]
	v_pk_fma_f32 v[46:47], v[88:89], v[162:163], v[46:47] op_sel_hi:[0,1,1]
	v_pk_fma_f32 v[44:45], v[86:87], v[162:163], v[44:45] op_sel_hi:[0,1,1]
	v_pk_fma_f32 v[40:41], v[82:83], v[162:163], v[40:41] op_sel_hi:[0,1,1]
	v_pk_fma_f32 v[38:39], v[90:91], v[160:161], v[38:39] op_sel_hi:[0,1,1]
	v_pk_fma_f32 v[30:31], v[88:89], v[160:161], v[30:31] op_sel_hi:[0,1,1]
	v_pk_fma_f32 v[28:29], v[86:87], v[160:161], v[28:29] op_sel_hi:[0,1,1]
	v_pk_fma_f32 v[24:25], v[82:83], v[160:161], v[24:25] op_sel_hi:[0,1,1]
	v_pk_fma_f32 v[18:19], v[90:91], v[84:85], v[18:19] op_sel_hi:[0,1,1]
	v_pk_fma_f32 v[16:17], v[88:89], v[84:85], v[16:17] op_sel_hi:[0,1,1]
	v_pk_fma_f32 v[14:15], v[86:87], v[84:85], v[14:15] op_sel_hi:[0,1,1]
	v_pk_fma_f32 v[12:13], v[82:83], v[84:85], v[12:13] op_sel_hi:[0,1,1]
	v_pk_fma_f32 v[50:51], v[100:101], v[196:197], v[50:51] op_sel_hi:[0,1,1]
	v_pk_fma_f32 v[26:27], v[98:99], v[196:197], v[26:27] op_sel_hi:[0,1,1]
	v_pk_fma_f32 v[22:23], v[96:97], v[196:197], v[22:23] op_sel_hi:[0,1,1]
	v_pk_fma_f32 v[20:21], v[92:93], v[196:197], v[20:21] op_sel_hi:[0,1,1]
	v_pk_fma_f32 v[48:49], v[100:101], v[168:169], v[48:49] op_sel_hi:[0,1,1]
	v_pk_fma_f32 v[46:47], v[98:99], v[168:169], v[46:47] op_sel_hi:[0,1,1]
	v_pk_fma_f32 v[44:45], v[96:97], v[168:169], v[44:45] op_sel_hi:[0,1,1]
	v_pk_fma_f32 v[40:41], v[92:93], v[168:169], v[40:41] op_sel_hi:[0,1,1]
	v_pk_fma_f32 v[38:39], v[100:101], v[166:167], v[38:39] op_sel_hi:[0,1,1]
	v_pk_fma_f32 v[30:31], v[98:99], v[166:167], v[30:31] op_sel_hi:[0,1,1]
	v_pk_fma_f32 v[28:29], v[96:97], v[166:167], v[28:29] op_sel_hi:[0,1,1]
	v_pk_fma_f32 v[24:25], v[92:93], v[166:167], v[24:25] op_sel_hi:[0,1,1]
	s_waitcnt vmcnt(20) lgkmcnt(15)
	v_pk_fma_f32 v[18:19], v[100:101], v[94:95], v[18:19] op_sel_hi:[0,1,1]
	v_pk_fma_f32 v[16:17], v[98:99], v[94:95], v[16:17] op_sel_hi:[0,1,1]
	v_pk_fma_f32 v[14:15], v[96:97], v[94:95], v[14:15] op_sel_hi:[0,1,1]
	v_pk_fma_f32 v[12:13], v[92:93], v[94:95], v[12:13] op_sel_hi:[0,1,1]
	s_waitcnt vmcnt(16) lgkmcnt(15)
	v_pk_fma_f32 v[50:51], v[110:111], v[198:199], v[50:51] op_sel_hi:[0,1,1]
	v_pk_fma_f32 v[26:27], v[108:109], v[198:199], v[26:27] op_sel_hi:[0,1,1]
	v_pk_fma_f32 v[22:23], v[106:107], v[198:199], v[22:23] op_sel_hi:[0,1,1]
	v_pk_fma_f32 v[20:21], v[102:103], v[198:199], v[20:21] op_sel_hi:[0,1,1]
	s_waitcnt vmcnt(16) lgkmcnt(15)
	v_pk_fma_f32 v[48:49], v[110:111], v[174:175], v[48:49] op_sel_hi:[0,1,1]
	v_pk_fma_f32 v[46:47], v[108:109], v[174:175], v[46:47] op_sel_hi:[0,1,1]
	v_pk_fma_f32 v[44:45], v[106:107], v[174:175], v[44:45] op_sel_hi:[0,1,1]
	v_pk_fma_f32 v[40:41], v[102:103], v[174:175], v[40:41] op_sel_hi:[0,1,1]
	s_waitcnt vmcnt(16) lgkmcnt(15)
	v_pk_fma_f32 v[38:39], v[110:111], v[170:171], v[38:39] op_sel_hi:[0,1,1]
	v_pk_fma_f32 v[30:31], v[108:109], v[170:171], v[30:31] op_sel_hi:[0,1,1]
	v_pk_fma_f32 v[28:29], v[106:107], v[170:171], v[28:29] op_sel_hi:[0,1,1]
	v_pk_fma_f32 v[24:25], v[102:103], v[170:171], v[24:25] op_sel_hi:[0,1,1]
	s_waitcnt vmcnt(16) lgkmcnt(15)
	v_pk_fma_f32 v[18:19], v[110:111], v[104:105], v[18:19] op_sel_hi:[0,1,1]
	v_pk_fma_f32 v[16:17], v[108:109], v[104:105], v[16:17] op_sel_hi:[0,1,1]
	v_pk_fma_f32 v[14:15], v[106:107], v[104:105], v[14:15] op_sel_hi:[0,1,1]
	v_pk_fma_f32 v[12:13], v[102:103], v[104:105], v[12:13] op_sel_hi:[0,1,1]
	s_waitcnt vmcnt(12) lgkmcnt(15)
	v_pk_fma_f32 v[50:51], v[124:125], v[200:201], v[50:51] op_sel_hi:[0,1,1]
	v_pk_fma_f32 v[26:27], v[120:121], v[200:201], v[26:27] op_sel_hi:[0,1,1]
	v_pk_fma_f32 v[22:23], v[118:119], v[200:201], v[22:23] op_sel_hi:[0,1,1]
	v_pk_fma_f32 v[20:21], v[114:115], v[200:201], v[20:21] op_sel_hi:[0,1,1]
	s_waitcnt vmcnt(12) lgkmcnt(14)
	v_pk_fma_f32 v[48:49], v[124:125], v[182:183], v[48:49] op_sel_hi:[0,1,1]
	v_pk_fma_f32 v[46:47], v[120:121], v[182:183], v[46:47] op_sel_hi:[0,1,1]
	v_pk_fma_f32 v[44:45], v[118:119], v[182:183], v[44:45] op_sel_hi:[0,1,1]
	v_pk_fma_f32 v[40:41], v[114:115], v[182:183], v[40:41] op_sel_hi:[0,1,1]
	s_waitcnt vmcnt(12) lgkmcnt(13)
	v_pk_fma_f32 v[38:39], v[124:125], v[180:181], v[38:39] op_sel_hi:[0,1,1]
	v_pk_fma_f32 v[30:31], v[120:121], v[180:181], v[30:31] op_sel_hi:[0,1,1]
	v_pk_fma_f32 v[28:29], v[118:119], v[180:181], v[28:29] op_sel_hi:[0,1,1]
	v_pk_fma_f32 v[24:25], v[114:115], v[180:181], v[24:25] op_sel_hi:[0,1,1]
	s_waitcnt vmcnt(12) lgkmcnt(12)
	v_pk_fma_f32 v[18:19], v[124:125], v[116:117], v[18:19] op_sel_hi:[0,1,1]
	v_pk_fma_f32 v[16:17], v[120:121], v[116:117], v[16:17] op_sel_hi:[0,1,1]
	v_pk_fma_f32 v[14:15], v[118:119], v[116:117], v[14:15] op_sel_hi:[0,1,1]
	v_pk_fma_f32 v[12:13], v[114:115], v[116:117], v[12:13] op_sel_hi:[0,1,1]
	s_waitcnt vmcnt(8) lgkmcnt(11)
	v_pk_fma_f32 v[50:51], v[136:137], v[208:209], v[50:51] op_sel_hi:[0,1,1]
	v_pk_fma_f32 v[26:27], v[134:135], v[208:209], v[26:27] op_sel_hi:[0,1,1]
	v_pk_fma_f32 v[22:23], v[132:133], v[208:209], v[22:23] op_sel_hi:[0,1,1]
	v_pk_fma_f32 v[20:21], v[128:129], v[208:209], v[20:21] op_sel_hi:[0,1,1]
	s_waitcnt vmcnt(8) lgkmcnt(10)
	v_pk_fma_f32 v[48:49], v[136:137], v[188:189], v[48:49] op_sel_hi:[0,1,1]
	v_pk_fma_f32 v[46:47], v[134:135], v[188:189], v[46:47] op_sel_hi:[0,1,1]
	v_pk_fma_f32 v[44:45], v[132:133], v[188:189], v[44:45] op_sel_hi:[0,1,1]
	v_pk_fma_f32 v[40:41], v[128:129], v[188:189], v[40:41] op_sel_hi:[0,1,1]
	s_waitcnt vmcnt(8) lgkmcnt(9)
	v_pk_fma_f32 v[38:39], v[136:137], v[186:187], v[38:39] op_sel_hi:[0,1,1]
	v_pk_fma_f32 v[30:31], v[134:135], v[186:187], v[30:31] op_sel_hi:[0,1,1]
	v_pk_fma_f32 v[28:29], v[132:133], v[186:187], v[28:29] op_sel_hi:[0,1,1]
	v_pk_fma_f32 v[24:25], v[128:129], v[186:187], v[24:25] op_sel_hi:[0,1,1]
	s_waitcnt vmcnt(8) lgkmcnt(8)
	v_pk_fma_f32 v[18:19], v[136:137], v[130:131], v[18:19] op_sel_hi:[0,1,1]
	v_pk_fma_f32 v[16:17], v[134:135], v[130:131], v[16:17] op_sel_hi:[0,1,1]
	v_pk_fma_f32 v[14:15], v[132:133], v[130:131], v[14:15] op_sel_hi:[0,1,1]
	v_pk_fma_f32 v[12:13], v[128:129], v[130:131], v[12:13] op_sel_hi:[0,1,1]
	s_waitcnt vmcnt(4) lgkmcnt(7)
	v_pk_fma_f32 v[50:51], v[152:153], v[210:211], v[50:51] op_sel_hi:[0,1,1]
	v_pk_fma_f32 v[26:27], v[148:149], v[210:211], v[26:27] op_sel_hi:[0,1,1]
	v_pk_fma_f32 v[22:23], v[146:147], v[210:211], v[22:23] op_sel_hi:[0,1,1]
	v_pk_fma_f32 v[20:21], v[142:143], v[210:211], v[20:21] op_sel_hi:[0,1,1]
	s_waitcnt vmcnt(4) lgkmcnt(6)
	v_pk_fma_f32 v[48:49], v[152:153], v[194:195], v[48:49] op_sel_hi:[0,1,1]
	v_pk_fma_f32 v[46:47], v[148:149], v[194:195], v[46:47] op_sel_hi:[0,1,1]
	v_pk_fma_f32 v[44:45], v[146:147], v[194:195], v[44:45] op_sel_hi:[0,1,1]
	v_pk_fma_f32 v[40:41], v[142:143], v[194:195], v[40:41] op_sel_hi:[0,1,1]
	s_waitcnt vmcnt(4) lgkmcnt(5)
	v_pk_fma_f32 v[38:39], v[152:153], v[192:193], v[38:39] op_sel_hi:[0,1,1]
	v_pk_fma_f32 v[30:31], v[148:149], v[192:193], v[30:31] op_sel_hi:[0,1,1]
	v_pk_fma_f32 v[28:29], v[146:147], v[192:193], v[28:29] op_sel_hi:[0,1,1]
	v_pk_fma_f32 v[24:25], v[142:143], v[192:193], v[24:25] op_sel_hi:[0,1,1]
	s_waitcnt vmcnt(4) lgkmcnt(4)
	v_pk_fma_f32 v[18:19], v[152:153], v[144:145], v[18:19] op_sel_hi:[0,1,1]
	v_pk_fma_f32 v[16:17], v[148:149], v[144:145], v[16:17] op_sel_hi:[0,1,1]
	v_pk_fma_f32 v[14:15], v[146:147], v[144:145], v[14:15] op_sel_hi:[0,1,1]
	v_pk_fma_f32 v[12:13], v[142:143], v[144:145], v[12:13] op_sel_hi:[0,1,1]
	s_waitcnt vmcnt(0) lgkmcnt(3)
	v_pk_fma_f32 v[50:51], v[158:159], v[212:213], v[50:51] op_sel_hi:[0,1,1]
	v_pk_fma_f32 v[26:27], v[206:207], v[212:213], v[26:27] op_sel_hi:[0,1,1]
	v_pk_fma_f32 v[22:23], v[204:205], v[212:213], v[22:23] op_sel_hi:[0,1,1]
	v_pk_fma_f32 v[20:21], v[202:203], v[212:213], v[20:21] op_sel_hi:[0,1,1]
	s_waitcnt vmcnt(0) lgkmcnt(2)
	v_pk_fma_f32 v[48:49], v[158:159], v[164:165], v[48:49] op_sel_hi:[0,1,1]
	v_pk_fma_f32 v[46:47], v[206:207], v[164:165], v[46:47] op_sel_hi:[0,1,1]
	v_pk_fma_f32 v[44:45], v[204:205], v[164:165], v[44:45] op_sel_hi:[0,1,1]
	v_pk_fma_f32 v[40:41], v[202:203], v[164:165], v[40:41] op_sel_hi:[0,1,1]
	s_waitcnt vmcnt(0) lgkmcnt(1)
	v_pk_fma_f32 v[38:39], v[158:159], v[122:123], v[38:39] op_sel_hi:[0,1,1]
	v_pk_fma_f32 v[30:31], v[206:207], v[122:123], v[30:31] op_sel_hi:[0,1,1]
	v_pk_fma_f32 v[28:29], v[204:205], v[122:123], v[28:29] op_sel_hi:[0,1,1]
	v_pk_fma_f32 v[24:25], v[202:203], v[122:123], v[24:25] op_sel_hi:[0,1,1]
	s_waitcnt vmcnt(0) lgkmcnt(0)
	v_pk_fma_f32 v[18:19], v[158:159], v[112:113], v[18:19] op_sel_hi:[0,1,1]
	v_pk_fma_f32 v[16:17], v[206:207], v[112:113], v[16:17] op_sel_hi:[0,1,1]
	v_pk_fma_f32 v[14:15], v[204:205], v[112:113], v[14:15] op_sel_hi:[0,1,1]
	v_pk_fma_f32 v[12:13], v[202:203], v[112:113], v[12:13] op_sel_hi:[0,1,1]
	v_add_u32_e32 v253, 0x200, v253
	s_cbranch_scc0 .LBB0_543
	v_cvt_f32_i32_e32 v4, s2
	s_ashr_i32 s5, s2, 31
	s_mov_b32 s4, s2
	s_lshl_b64 s[2:3], s[4:5], 14
	v_mul_f32_e32 v4, 0xc1447cbd, v4
	v_div_scale_f32 v32, s[8:9], s48, s48, v4
	v_rcp_f32_e32 v33, v32
	v_div_scale_f32 v34, vcc, v4, s48, v4
	s_add_u32 s2, s14, s2
	v_fma_f32 v36, -v32, v33, 1.0
	v_fmac_f32_e32 v33, v36, v33
	v_mul_f32_e32 v36, v34, v33
	v_fma_f32 v42, -v32, v36, v34
	v_fmac_f32_e32 v36, v42, v33
	v_fma_f32 v32, -v32, v36, v34
	v_div_fmas_f32 v32, v32, v33, v36
	v_div_fixup_f32 v4, v32, s48, v4
	v_add_f32_e32 v34, 0xc0447cbd, v4
	v_mul_f32_e64 v4, v1, |v34|
	v_mul_f32_e32 v32, 0x3fb8aa3b, v4
	v_fma_f32 v33, v4, s49, -v32
	v_rndne_f32_e32 v36, v32
	v_fmac_f32_e32 v33, 0x32a5705f, v4
	v_sub_f32_e32 v32, v32, v36
	v_add_f32_e32 v32, v32, v33
	v_exp_f32_e32 v32, v32
	v_cvt_i32_f32_e32 v33, v36
	v_cmp_ngt_f32_e32 vcc, s52, v4
	s_addc_u32 s3, s15, s3
	v_ldexp_f32 v32, v32, v33
	v_cndmask_b32_e32 v32, 0, v32, vcc
	v_cmp_nlt_f32_e32 vcc, s53, v4
	v_lshlrev_b32_e32 v4, 1, v0
	s_nop 0
	v_cndmask_b32_e32 v36, v217, v32, vcc
	v_mul_f32_e32 v33, v36, v51
	v_lshlrev_b32_e32 v32, 1, v6
	s_and_saveexec_b64 s[8:9], s[86:87]
	s_xor_b64 s[8:9], exec, s[8:9]
	s_cbranch_execz .LBB0_546
	v_bfe_u32 v43, v33, 16, 1
	v_mul_f32_e32 v42, v36, v50
	v_add3_u32 v33, v33, v43, s54
	global_store_short_d16_hi v32, v33, s[2:3] offset:2048
	v_bfe_u32 v33, v42, 16, 1
	v_add3_u32 v33, v42, v33, s54
	global_store_short_d16_hi v4, v33, s[2:3] offset:4094
